# GEMM k-loops: removed the lgkmcnt wait in front of the first barrier of a k-step (all fragment reads already consumed behind counted waits)
# speedup vs baseline: 1.0130x; 1.0130x over previous
; template <class Epi>
; __device__ __forceinline__ void gemm_tile64(const bf16_t* A, const bf16_t* Bt, int tm, int tn, const Epi& epi, char* smem, const float* ssq, int nparts) {
;     ...
;     auto gload = [&](int kt, Slab& sl) {
; #pragma unroll
;         for (int i = 0; i < 4; ++i) { sl.a[i] = *(const u32x4*)(Ap + (size_t)(32 * i) * K + kt * 64); sl.b[i] = *(const u32x4*)(Bp + (size_t)(32 * i) * K + kt * 64); }
;     };
;     auto sstore = [&](const Slab& sl) {
; #pragma unroll
;         for (int i = 0; i < 4; ++i) {
;             const int r = lrow + 32 * i;
;             *(u32x4*)(sA + r * 64 + ((lc8 ^ ((r >> 1) & 7)) * 8)) = sl.a[i];
;             const int rs = (r & 64) | (((r >> 2) & 3) << 4) | (((r >> 4) & 3) << 2) | (r & 3);
;             *(u32x4*)(sB + rs * 64 + ((lc8 ^ ((rs >> 1) & 7)) * 8)) = sl.b[i];
;         }
;     };
;     auto compute = [&]() {
; #pragma unroll
;         for (int ks = 0; ks < 2; ++ks) {
;             bf16x8 af[4], bfr[4];
; #pragma unroll
;             for (int m = 0; m < 4; ++m) { const int r = wr * 64 + m * 16 + fr; af[m] = *(const bf16x8*)(sA + r * 64 + (((ks * 4 + fq) ^ ((r >> 1) & 7)) * 8)); }
; #pragma unroll
;             for (int n = 0; n < 4; ++n) { const int r = wc * 64 + n * 16 + fr; bfr[n] = *(const bf16x8*)(sB + r * 64 + (((ks * 4 + fq) ^ ((r >> 1) & 7)) * 8)); }
; #pragma unroll
;             for (int m = 0; m < 4; ++m)
; #pragma unroll
;                 for (int n = 0; n < 4; ++n) acc[m][n] = __builtin_amdgcn_mfma_f32_16x16x32_bf16(bfr[n], af[m], acc[m][n], 0, 0, 0);
;         }
;     };
;     Slab s0;
;     gload(0, s0);
;     for (int kt = 0; kt < 16; ++kt) {
;         __syncthreads(); sstore(s0); __syncthreads();
;         gload(min(kt + 1, 15), s0);
.LBB0_51:
	s_barrier
	s_waitcnt vmcnt(7)
	ds_write_b128 v100, v[64:67]
	s_waitcnt vmcnt(6)
	ds_write_b128 v101, v[68:71] offset:16384
	s_waitcnt vmcnt(5)
	ds_write_b128 v102, v[72:75]
	s_waitcnt vmcnt(4)
	ds_write_b128 v103, v[76:79] offset:16384
	s_waitcnt vmcnt(3)
	ds_write_b128 v104, v[156:159]
	s_waitcnt vmcnt(2)
	ds_write_b128 v105, v[160:163] offset:16384
	s_waitcnt vmcnt(1)
	ds_write_b128 v106, v[148:151]
	s_waitcnt vmcnt(0)
	ds_write_b128 v107, v[152:155] offset:16384
	s_add_i32 s13, s13, 1
	s_waitcnt lgkmcnt(0)
	s_barrier
	s_setprio 2
	ds_read_b128 v[80:83], v109 offset:16384
	ds_read_b128 v[84:87], v109 offset:18432
	ds_read_b128 v[88:91], v108
	ds_read_b128 v[92:95], v108 offset:2048
	ds_read_b128 v[116:119], v109 offset:20480
	ds_read_b128 v[120:123], v109 offset:22528
	s_cmp_eq_u32 s13, 17
	s_cbranch_scc1 .Lgs_nopf
	global_load_dwordx4 v[64:67], v135, s[98:99]
	global_load_dwordx4 v[68:71], v135, s[20:21]
	global_load_dwordx4 v[72:75], v136, s[98:99]
	global_load_dwordx4 v[76:79], v136, s[20:21]
	global_load_dwordx4 v[156:159], v137, s[98:99]
	global_load_dwordx4 v[160:163], v137, s[20:21]
	global_load_dwordx4 v[148:151], v138, s[98:99]
	global_load_dwordx4 v[152:155], v138, s[20:21]
	s_add_u32 s98, s98, 0x80
	s_addc_u32 s99, s99, 0
	s_add_u32 s20, s20, 0x80
	s_addc_u32 s21, s21, 0

; template <class Epi>
; __device__ __forceinline__ void gemm_tile64(const bf16_t* A, const bf16_t* Bt, int tm, int tn, const Epi& epi, char* smem, const float* ssq, int nparts) {
;     ...
;     auto gload = [&](int kt, Slab& sl) {
; #pragma unroll
;         for (int i = 0; i < 4; ++i) { sl.a[i] = *(const u32x4*)(Ap + (size_t)(32 * i) * K + kt * 64); sl.b[i] = *(const u32x4*)(Bp + (size_t)(32 * i) * K + kt * 64); }
;     };
;     auto sstore = [&](const Slab& sl) {
; #pragma unroll
;         for (int i = 0; i < 4; ++i) {
;             const int r = lrow + 32 * i;
;             *(u32x4*)(sA + r * 64 + ((lc8 ^ ((r >> 1) & 7)) * 8)) = sl.a[i];
;             const int rs = (r & 64) | (((r >> 2) & 3) << 4) | (((r >> 4) & 3) << 2) | (r & 3);
;             *(u32x4*)(sB + rs * 64 + ((lc8 ^ ((rs >> 1) & 7)) * 8)) = sl.b[i];
;         }
;     };
;     auto compute = [&]() {
; #pragma unroll
;         for (int ks = 0; ks < 2; ++ks) {
;             bf16x8 af[4], bfr[4];
; #pragma unroll
;             for (int m = 0; m < 4; ++m) { const int r = wr * 64 + m * 16 + fr; af[m] = *(const bf16x8*)(sA + r * 64 + (((ks * 4 + fq) ^ ((r >> 1) & 7)) * 8)); }
; #pragma unroll
;             for (int n = 0; n < 4; ++n) { const int r = wc * 64 + n * 16 + fr; bfr[n] = *(const bf16x8*)(sB + r * 64 + (((ks * 4 + fq) ^ ((r >> 1) & 7)) * 8)); }
; #pragma unroll
;             for (int m = 0; m < 4; ++m)
; #pragma unroll
;                 for (int n = 0; n < 4; ++n) acc[m][n] = __builtin_amdgcn_mfma_f32_16x16x32_bf16(bfr[n], af[m], acc[m][n], 0, 0, 0);
;         }
;     };
;     Slab s0;
;     gload(0, s0);
;     for (int kt = 0; kt < 16; ++kt) {
;         __syncthreads(); sstore(s0); __syncthreads();
;         gload(min(kt + 1, 15), s0);
.LBB0_71:
	s_barrier
	s_waitcnt vmcnt(7)
	ds_write_b128 v100, v[64:67]
	s_waitcnt vmcnt(6)
	ds_write_b128 v101, v[68:71] offset:16384
	s_waitcnt vmcnt(5)
	ds_write_b128 v102, v[72:75]
	s_waitcnt vmcnt(4)
	ds_write_b128 v103, v[76:79] offset:16384
	s_waitcnt vmcnt(3)
	ds_write_b128 v104, v[156:159]
	s_waitcnt vmcnt(2)
	ds_write_b128 v105, v[160:163] offset:16384
	s_waitcnt vmcnt(1)
	ds_write_b128 v106, v[148:151]
	s_waitcnt vmcnt(0)
	ds_write_b128 v107, v[152:155] offset:16384
	s_add_i32 s1, s1, 1
	s_waitcnt lgkmcnt(0)
	s_barrier
	s_setprio 2
	ds_read_b128 v[80:83], v109 offset:16384
	ds_read_b128 v[84:87], v109 offset:18432
	ds_read_b128 v[88:91], v108
	ds_read_b128 v[92:95], v108 offset:2048
	ds_read_b128 v[116:119], v109 offset:20480
	ds_read_b128 v[120:123], v109 offset:22528
	s_cmp_eq_u32 s1, 17
	s_cbranch_scc1 .Lgo_nopf
	global_load_dwordx4 v[64:67], v135, s[98:99]
	global_load_dwordx4 v[68:71], v135, s[20:21]
	global_load_dwordx4 v[72:75], v136, s[98:99]
	global_load_dwordx4 v[76:79], v136, s[20:21]
	global_load_dwordx4 v[156:159], v137, s[98:99]
	global_load_dwordx4 v[160:163], v137, s[20:21]
	global_load_dwordx4 v[148:151], v138, s[98:99]
	global_load_dwordx4 v[152:155], v138, s[20:21]
	s_add_u32 s98, s98, 0x80
	s_addc_u32 s99, s99, 0
	s_add_u32 s20, s20, 0x80
	s_addc_u32 s21, s21, 0

; template <class Epi>
; __device__ __forceinline__ void gemm_tile64(const bf16_t* A, const bf16_t* Bt, int tm, int tn, const Epi& epi, char* smem, const float* ssq, int nparts) {
;     ...
;     auto gload = [&](int kt, Slab& sl) {
; #pragma unroll
;         for (int i = 0; i < 4; ++i) { sl.a[i] = *(const u32x4*)(Ap + (size_t)(32 * i) * K + kt * 64); sl.b[i] = *(const u32x4*)(Bp + (size_t)(32 * i) * K + kt * 64); }
;     };
;     auto sstore = [&](const Slab& sl) {
; #pragma unroll
;         for (int i = 0; i < 4; ++i) {
;             const int r = lrow + 32 * i;
;             *(u32x4*)(sA + r * 64 + ((lc8 ^ ((r >> 1) & 7)) * 8)) = sl.a[i];
;             const int rs = (r & 64) | (((r >> 2) & 3) << 4) | (((r >> 4) & 3) << 2) | (r & 3);
;             *(u32x4*)(sB + rs * 64 + ((lc8 ^ ((rs >> 1) & 7)) * 8)) = sl.b[i];
;         }
;     };
;     auto compute = [&]() {
; #pragma unroll
;         for (int ks = 0; ks < 2; ++ks) {
;             bf16x8 af[4], bfr[4];
; #pragma unroll
;             for (int m = 0; m < 4; ++m) { const int r = wr * 64 + m * 16 + fr; af[m] = *(const bf16x8*)(sA + r * 64 + (((ks * 4 + fq) ^ ((r >> 1) & 7)) * 8)); }
; #pragma unroll
;             for (int n = 0; n < 4; ++n) { const int r = wc * 64 + n * 16 + fr; bfr[n] = *(const bf16x8*)(sB + r * 64 + (((ks * 4 + fq) ^ ((r >> 1) & 7)) * 8)); }
; #pragma unroll
;             for (int m = 0; m < 4; ++m)
; #pragma unroll
;                 for (int n = 0; n < 4; ++n) acc[m][n] = __builtin_amdgcn_mfma_f32_16x16x32_bf16(bfr[n], af[m], acc[m][n], 0, 0, 0);
;         }
;     };
;     Slab s0;
;     gload(0, s0);
;     for (int kt = 0; kt < 16; ++kt) {
;         __syncthreads(); sstore(s0); __syncthreads();
;         gload(min(kt + 1, 15), s0);
.LBB0_376:
	s_barrier
	s_waitcnt vmcnt(7)
	ds_write_b128 v100, v[64:67]
	s_waitcnt vmcnt(6)
	ds_write_b128 v101, v[68:71] offset:16384
	s_waitcnt vmcnt(5)
	ds_write_b128 v102, v[72:75]
	s_waitcnt vmcnt(4)
	ds_write_b128 v103, v[76:79] offset:16384
	s_waitcnt vmcnt(3)
	ds_write_b128 v104, v[156:159]
	s_waitcnt vmcnt(2)
	ds_write_b128 v105, v[160:163] offset:16384
	s_waitcnt vmcnt(1)
	ds_write_b128 v106, v[148:151]
	s_waitcnt vmcnt(0)
	ds_write_b128 v107, v[152:155] offset:16384
	s_add_i32 s0, s0, 1
	s_waitcnt lgkmcnt(0)
	s_barrier
	s_setprio 2
	ds_read_b128 v[80:83], v109 offset:16384
	ds_read_b128 v[84:87], v109 offset:18432
	ds_read_b128 v[88:91], v108
	ds_read_b128 v[92:95], v108 offset:2048
	ds_read_b128 v[116:119], v109 offset:20480
	ds_read_b128 v[120:123], v109 offset:22528
	s_cmp_eq_u32 s0, 17
	s_cbranch_scc1 .Lgi_nopf
	global_load_dwordx4 v[64:67], v135, s[98:99]
	global_load_dwordx4 v[68:71], v135, s[20:21]
	global_load_dwordx4 v[72:75], v136, s[98:99]
	global_load_dwordx4 v[76:79], v136, s[20:21]
	global_load_dwordx4 v[156:159], v137, s[98:99]
	global_load_dwordx4 v[160:163], v137, s[20:21]
	global_load_dwordx4 v[148:151], v138, s[98:99]
	global_load_dwordx4 v[152:155], v138, s[20:21]
	s_add_u32 s98, s98, 0x80
	s_addc_u32 s99, s99, 0
	s_add_u32 s20, s20, 0x80
	s_addc_u32 s21, s21, 0
